# hg S2 tail: GI row reads hoisted (gj0 read at the start of S2, gj1 issued before the first P block), two exposed LDS round trips removed
# baseline (speedup 1.0000x reference)
; __device__ __forceinline__ unsigned cvt_pk_bf16(float lo, float hi) { unsigned r; asm("v_cvt_pk_bf16_f32 %0, %1, %2" : "=v"(r) : "v"(lo), "v"(hi)); return r; }
; template <int DK, int DV, bool SEPQ> ...
;     ...
;         for (int vt = 0; vt < NVT; ++vt) { const f32x4 s = S[ct][vt]; u32x2 w; w.x = cvt_pk_bf16(s[0], s[1]); w.y = cvt_pk_bf16(s[2], s[3]);
;             *(u32x2*)(ST + (16 * vt + fr) * LQ + 16 * (wid * NCTW + ct) + 4 * fq) = w; }
;     __syncthreads();
;     {
;         const float gi_i = GI[16 * m + fr];
;         const int n0 = 2 * hw, n1 = 2 * hw + 1; const bool do0 = n0 <= m, do1 = n1 <= m;
;         f32x4 acc0 = {0.f, 0.f, 0.f, 0.f}, acc1 = {0.f, 0.f, 0.f, 0.f};
; #pragma unroll
;         for (int vt = 0; vt < NVTW; ++vt) O[vt] = (f32x4){0.f, 0.f, 0.f, 0.f};
; #pragma unroll
;         for (int ks = 0; ks < DK / 32; ++ks) {
;             const bf16x8 qf = *(const bf16x8*)(QA + (16 * m + fr) * LQ + 32 * ks + 8 * fq);
;             if (do0) { const bf16x8 kf = *(const bf16x8*)(KB + (16 * n0 + fr) * LQ + 32 * ks + 8 * fq); acc0 = __builtin_amdgcn_mfma_f32_16x16x32_bf16(kf, qf, acc0, 0, 0, 0); }
;             if (do1) { const bf16x8 kf = *(const bf16x8*)(KB + (16 * n1 + fr) * LQ + 32 * ks + 8 * fq); acc1 = __builtin_amdgcn_mfma_f32_16x16x32_bf16(kf, qf, acc1, 0, 0, 0); }
;             bf16x8 qs = qf; if (SEPQ) qs = *(const bf16x8*)(QS + (16 * m + fr) * LQ + 32 * ks + 8 * fq);
; #pragma unroll
;             for (int vt = 0; vt < NVTW; ++vt) { const bf16x8 sf = *(const bf16x8*)(ST + (16 * (hw * NVTW + vt) + fr) * LQ + 32 * ks + 8 * fq); O[vt] = __builtin_amdgcn_mfma_f32_16x16x32_bf16(sf, qs, O[vt], 0, 0, 0); }
;         }
; #pragma unroll
;         for (int nn = 0; nn < 2; ++nn) {
;             const int n = 2 * hw + nn; const f32x4 acc = nn == 0 ? acc0 : acc1;
;             const f32x4 gj = *(const f32x4*)(GI + 16 * n + 4 * fq); const int i = 16 * m + fr, j0 = 16 * n + 4 * fq; float p[4];
; #pragma unroll
;             for (int e = 0; e < 4; ++e) p[e] = (j0 + e <= i) ? acc[e] * __expf(gi_i - gj[e]) : 0.f;
;             u32x2 w; w.x = cvt_pk_bf16(p[0], p[1]); w.y = cvt_pk_bf16(p[2], p[3]); *(u32x2*)(P + (16 * m + fr) * LJ + j0) = w;
;         }
;         const float ei = __expf(gi_i);
.LBB0_420:
	s_lshl_b32 s54, s62, 9
	s_mov_b32 s55, s12
	v_lshl_add_u64 v[218:219], v[114:115], 0, s[54:55]
	global_load_dwordx4 v[202:205], v[218:219], off
	global_load_dwordx4 v[206:209], v[218:219], off offset:64
	global_load_dwordx4 v[210:213], v[218:219], off offset:128
	global_load_dwordx4 v[214:217], v[218:219], off offset:192
	v_cvt_pk_bf16_f32 v50, v18, v19
	v_cvt_pk_bf16_f32 v51, v20, v21
	ds_write_b64 v169, v[50:51]
	v_cvt_pk_bf16_f32 v50, v22, v23
	v_cvt_pk_bf16_f32 v51, v24, v25
	ds_write_b64 v169, v[50:51] offset:4352
	v_cvt_pk_bf16_f32 v50, v26, v27
	v_cvt_pk_bf16_f32 v51, v28, v29
	ds_write_b64 v169, v[50:51] offset:8704
	v_cvt_pk_bf16_f32 v50, v30, v31
	v_cvt_pk_bf16_f32 v51, v32, v33
	ds_write_b64 v169, v[50:51] offset:13056
	v_cvt_pk_bf16_f32 v50, v34, v35
	v_cvt_pk_bf16_f32 v51, v36, v37
	ds_write_b64 v169, v[50:51] offset:17408
	v_cvt_pk_bf16_f32 v50, v38, v39
	v_cvt_pk_bf16_f32 v51, v40, v41
	ds_write_b64 v169, v[50:51] offset:21760
	v_cvt_pk_bf16_f32 v50, v42, v43
	v_cvt_pk_bf16_f32 v51, v44, v45
	ds_write_b64 v169, v[50:51] offset:26112
	v_cvt_pk_bf16_f32 v50, v46, v47
	v_cvt_pk_bf16_f32 v51, v48, v49
	ds_write_b64 v169, v[50:51] offset:30464
	s_waitcnt lgkmcnt(0)
	s_barrier
	ds_read_b64 v[192:193], v141
	ds_read_b64 v[196:197], v141 offset:8
	ds_read_b32 v16, v138
	ds_read_b128 v[218:221], v139
	ds_read_b128 v[222:225], v140 offset:17408
	ds_read_b128 v[226:229], v140 offset:21760
	ds_read_b128 v[242:245], v139 offset:34816
	ds_read_b128 v[246:249], v174
	ds_read_b128 v[74:77], v174 offset:4352
	ds_read_b128 v[176:179], v174 offset:8704
	ds_read_b128 v[180:183], v174 offset:13056
	ds_read_b128 v[230:233], v139 offset:64
	ds_read_b128 v[234:237], v140 offset:17472
	ds_read_b128 v[238:241], v140 offset:21824
	s_waitcnt lgkmcnt(8)
	v_mfma_f32_16x16x32_bf16 v[54:57], v[222:225], v[218:221], 0
	v_mfma_f32_16x16x32_bf16 v[50:53], v[226:229], v[218:221], 0
	s_waitcnt lgkmcnt(3)
	v_mfma_f32_16x16x32_bf16 v[58:61], v[246:249], v[242:245], 0
	v_mfma_f32_16x16x32_bf16 v[62:65], v[74:77], v[242:245], 0
	v_mfma_f32_16x16x32_bf16 v[66:69], v[176:179], v[242:245], 0
	v_mfma_f32_16x16x32_bf16 v[70:73], v[180:183], v[242:245], 0
	ds_read_b128 v[242:245], v139 offset:34880
	ds_read_b128 v[246:249], v174 offset:64
	ds_read_b128 v[74:77], v174 offset:4416
	ds_read_b128 v[176:179], v174 offset:8768
	ds_read_b128 v[180:183], v174 offset:13120
	ds_read_b128 v[218:221], v139 offset:128
	ds_read_b128 v[222:225], v140 offset:17536
	ds_read_b128 v[226:229], v140 offset:21888
	s_waitcnt lgkmcnt(8)
	v_mfma_f32_16x16x32_bf16 v[54:57], v[234:237], v[230:233], v[54:57]
	v_mfma_f32_16x16x32_bf16 v[50:53], v[238:241], v[230:233], v[50:53]
	s_waitcnt lgkmcnt(3)
	v_mfma_f32_16x16x32_bf16 v[58:61], v[246:249], v[242:245], v[58:61]
	v_mfma_f32_16x16x32_bf16 v[62:65], v[74:77], v[242:245], v[62:65]
	v_mfma_f32_16x16x32_bf16 v[66:69], v[176:179], v[242:245], v[66:69]
	v_mfma_f32_16x16x32_bf16 v[70:73], v[180:183], v[242:245], v[70:73]
	ds_read_b128 v[242:245], v139 offset:34944
	ds_read_b128 v[246:249], v174 offset:128
	ds_read_b128 v[74:77], v174 offset:4480
	ds_read_b128 v[176:179], v174 offset:8832
	ds_read_b128 v[180:183], v174 offset:13184
	ds_read_b128 v[230:233], v139 offset:192
	ds_read_b128 v[234:237], v140 offset:17600
	ds_read_b128 v[238:241], v140 offset:21952
	s_waitcnt lgkmcnt(8)
	v_mfma_f32_16x16x32_bf16 v[54:57], v[222:225], v[218:221], v[54:57]
	v_mfma_f32_16x16x32_bf16 v[50:53], v[226:229], v[218:221], v[50:53]
	s_waitcnt lgkmcnt(3)
	v_mfma_f32_16x16x32_bf16 v[58:61], v[246:249], v[242:245], v[58:61]
	v_mfma_f32_16x16x32_bf16 v[62:65], v[74:77], v[242:245], v[62:65]
	v_mfma_f32_16x16x32_bf16 v[66:69], v[176:179], v[242:245], v[66:69]
	v_mfma_f32_16x16x32_bf16 v[70:73], v[180:183], v[242:245], v[70:73]
	ds_read_b128 v[242:245], v139 offset:35008
	ds_read_b128 v[246:249], v174 offset:192
	ds_read_b128 v[74:77], v174 offset:4544
	ds_read_b128 v[176:179], v174 offset:8896
	ds_read_b128 v[180:183], v174 offset:13248
	s_waitcnt lgkmcnt(5)
	v_mfma_f32_16x16x32_bf16 v[54:57], v[234:237], v[230:233], v[54:57]
	v_mfma_f32_16x16x32_bf16 v[50:53], v[238:241], v[230:233], v[50:53]
	s_waitcnt lgkmcnt(0)
	v_mfma_f32_16x16x32_bf16 v[58:61], v[246:249], v[242:245], v[58:61]
	v_mfma_f32_16x16x32_bf16 v[62:65], v[74:77], v[242:245], v[62:65]
	v_mfma_f32_16x16x32_bf16 v[66:69], v[176:179], v[242:245], v[66:69]
	v_mfma_f32_16x16x32_bf16 v[70:73], v[180:183], v[242:245], v[70:73]
	s_nop 7
	v_readlane_b32 s52, v255, 14
	v_readlane_b32 s53, v255, 15
	ds_read_b128 v[74:77], v141 offset:64
	s_waitcnt lgkmcnt(1)
	v_sub_f32_e32 v170, v16, v192
	v_mul_f32_e32 v170, 0x3fb8aa3b, v170
	v_exp_f32_e32 v170, v170
	s_nop 0
	v_mul_f32_e32 v54, v54, v170
	v_sub_f32_e32 v170, v16, v193
	v_mul_f32_e32 v170, 0x3fb8aa3b, v170
	v_exp_f32_e32 v170, v170
	v_cndmask_b32_e64 v54, v54, 0, s[52:53]
	v_readlane_b32 s52, v255, 16
	v_readlane_b32 s53, v255, 17
	v_mul_f32_e32 v55, v55, v170
	v_sub_f32_e32 v170, v16, v196
	v_mul_f32_e32 v170, 0x3fb8aa3b, v170
	v_exp_f32_e32 v170, v170
	v_cndmask_b32_e64 v55, 0, v55, s[52:53]
	v_readlane_b32 s52, v255, 18
	v_readlane_b32 s53, v255, 19
	v_mul_f32_e32 v56, v56, v170
	v_sub_f32_e32 v170, v16, v197
	v_mul_f32_e32 v170, 0x3fb8aa3b, v170
	v_exp_f32_e32 v170, v170
	v_cndmask_b32_e64 v56, v56, 0, s[52:53]
	v_readlane_b32 s52, v255, 20
	v_readlane_b32 s53, v255, 21
	v_mul_f32_e32 v57, v57, v170
	v_cvt_pk_bf16_f32 v54, v54, v55
	s_nop 0
	v_cndmask_b32_e64 v57, v57, 0, s[52:53]
	v_cvt_pk_bf16_f32 v55, v56, v57
	ds_write_b64 v142, v[54:55]
	v_readlane_b32 s52, v255, 22
	v_readlane_b32 s53, v255, 23
	s_waitcnt lgkmcnt(1)
; __device__ __forceinline__ unsigned cvt_pk_bf16(float lo, float hi) { unsigned r; asm("v_cvt_pk_bf16_f32 %0, %1, %2" : "=v"(r) : "v"(lo), "v"(hi)); return r; }
; template <int DK, int DV, bool SEPQ> ...
;     ...
;         for (int nn = 0; nn < 2; ++nn) {
;             const int n = 2 * hw + nn; const f32x4 acc = nn == 0 ? acc0 : acc1;
;             const f32x4 gj = *(const f32x4*)(GI + 16 * n + 4 * fq); const int i = 16 * m + fr, j0 = 16 * n + 4 * fq; float p[4];
; #pragma unroll
;             for (int e = 0; e < 4; ++e) p[e] = (j0 + e <= i) ? acc[e] * __expf(gi_i - gj[e]) : 0.f;
;             u32x2 w; w.x = cvt_pk_bf16(p[0], p[1]); w.y = cvt_pk_bf16(p[2], p[3]); *(u32x2*)(P + (16 * m + fr) * LJ + j0) = w;
;         }
;         const float ei = __expf(gi_i);
; #pragma unroll
;         for (int vt = 0; vt < NVTW; ++vt) O[vt] = O[vt] * ei;
;     }
;     __syncthreads();
; #pragma unroll
;     for (int ks = 0; ks < 2; ++ks) { const bf16x8 pf = *(const bf16x8*)(P + (16 * m + fr) * LJ + 32 * ks + 8 * fq);
; #pragma unroll
;         for (int vt = 0; vt < NVTW; ++vt) { const bf16x8 vf = *(const bf16x8*)(VT + (16 * (hw * NVTW + vt) + fr) * LJ + 32 * ks + 8 * fq); O[vt] = __builtin_amdgcn_mfma_f32_16x16x32_bf16(vf, pf, O[vt], 0, 0, 0); } }
; #pragma unroll
;     for (int ct = 0; ct < NCTW; ++ct) { const int ctg = wid * NCTW + ct; const f32x4 dec = *(const f32x4*)(SDEC + 16 * ctg + 4 * fq);
; #pragma unroll
;         for (int vt = 0; vt < NVT; ++vt) S[ct][vt] = S[ct][vt] * dec;
; #pragma unroll
;         for (int ks = 0; ks < 2; ++ks) { const bf16x8 kf = *(const bf16x8*)(KT + (16 * ctg + fr) * LJ + 32 * ks + 8 * fq);
; #pragma unroll
;             for (int vt = 0; vt < NVT; ++vt) { const bf16x8 vf = *(const bf16x8*)(VT2 + (16 * vt + fr) * LJ + 32 * ks + 8 * fq); S[ct][vt] = __builtin_amdgcn_mfma_f32_16x16x32_bf16(kf, vf, S[ct][vt], 0, 0, 0); } } }
; __device__ __forceinline__ void hg_block(ArgsP a_, int jl, unsigned char* smem) { const ArgsP a = a_;
;     ...
;         { float ss = 0.f;
; #pragma unroll
;           for (int vt = 0; vt < 4; ++vt) ss += (O[vt][0] * O[vt][0] + O[vt][1] * O[vt][1]) + (O[vt][2] * O[vt][2] + O[vt][3] * O[vt][3]);
;           ss += __shfl_xor(ss, 16); ss += __shfl_xor(ss, 32); if (fq == 0) RSm[irow * 2 + hw] = ss; }
	v_sub_f32_e32 v170, v16, v74
	v_mul_f32_e32 v170, 0x3fb8aa3b, v170
	v_exp_f32_e32 v170, v170
	s_nop 0
	v_mul_f32_e32 v50, v50, v170
	v_sub_f32_e32 v170, v16, v75
	v_mul_f32_e32 v170, 0x3fb8aa3b, v170
	v_exp_f32_e32 v170, v170
	v_cndmask_b32_e64 v50, v50, 0, s[52:53]
	v_readlane_b32 s52, v255, 24
	v_readlane_b32 s53, v255, 25
	v_mul_f32_e32 v51, v51, v170
	v_sub_f32_e32 v170, v16, v76
	v_mul_f32_e32 v170, 0x3fb8aa3b, v170
	v_exp_f32_e32 v170, v170
	v_cndmask_b32_e64 v51, 0, v51, s[52:53]
	v_readlane_b32 s52, v255, 26
	v_readlane_b32 s53, v255, 27
	v_mul_f32_e32 v52, v52, v170
	v_sub_f32_e32 v170, v16, v77
	v_mul_f32_e32 v170, 0x3fb8aa3b, v170
	v_exp_f32_e32 v170, v170
	v_mul_f32_e32 v16, 0x3fb8aa3b, v16
	v_exp_f32_e32 v16, v16
	v_cndmask_b32_e64 v52, v52, 0, s[52:53]
	v_readlane_b32 s52, v255, 28
	v_mul_f32_e32 v53, v53, v170
	v_readlane_b32 s53, v255, 29
	v_cvt_pk_bf16_f32 v50, v50, v51
	v_pk_mul_f32 v[54:55], v[16:17], v[62:63] op_sel_hi:[0,1]
	v_pk_mul_f32 v[56:57], v[16:17], v[64:65] op_sel_hi:[0,1]
	v_cndmask_b32_e64 v53, v53, 0, s[52:53]
	v_cvt_pk_bf16_f32 v51, v52, v53
	ds_write_b64 v142, v[50:51] offset:32
	v_pk_mul_f32 v[50:51], v[16:17], v[58:59] op_sel_hi:[0,1]
	v_pk_mul_f32 v[52:53], v[16:17], v[60:61] op_sel_hi:[0,1]
	v_pk_mul_f32 v[58:59], v[16:17], v[66:67] op_sel_hi:[0,1]
	v_pk_mul_f32 v[60:61], v[16:17], v[68:69] op_sel_hi:[0,1]
	v_pk_mul_f32 v[62:63], v[16:17], v[70:71] op_sel_hi:[0,1]
	v_pk_mul_f32 v[64:65], v[16:17], v[72:73] op_sel_hi:[0,1]
	s_waitcnt lgkmcnt(0)
	s_barrier
	ds_read_b128 v[218:221], v143
	ds_read_b128 v[222:225], v143 offset:64
	ds_read_b128 v[226:229], v184
	ds_read_b128 v[230:233], v185 offset:2304
	ds_read_b128 v[234:237], v184 offset:4608
	ds_read_b128 v[238:241], v185 offset:6912
	ds_read_b128 v[242:245], v184 offset:64
	ds_read_b128 v[246:249], v185 offset:2368
	ds_read_b128 v[74:77], v184 offset:4672
	ds_read_b128 v[176:179], v185 offset:6976
	s_waitcnt lgkmcnt(7)
	v_mfma_f32_16x16x32_bf16 v[50:53], v[226:229], v[218:221], v[50:53]
	s_waitcnt lgkmcnt(6)
	v_mfma_f32_16x16x32_bf16 v[54:57], v[230:233], v[218:221], v[54:57]
	s_waitcnt lgkmcnt(5)
	v_mfma_f32_16x16x32_bf16 v[70:73], v[234:237], v[218:221], v[58:61]
	s_waitcnt lgkmcnt(4)
	v_mfma_f32_16x16x32_bf16 v[66:69], v[238:241], v[218:221], v[62:65]
	s_waitcnt lgkmcnt(3)
	v_mfma_f32_16x16x32_bf16 v[62:65], v[242:245], v[222:225], v[50:53]
	s_waitcnt lgkmcnt(2)
	v_mfma_f32_16x16x32_bf16 v[58:61], v[246:249], v[222:225], v[54:57]
	s_waitcnt lgkmcnt(1)
	v_mfma_f32_16x16x32_bf16 v[54:57], v[74:77], v[222:225], v[70:73]
	s_waitcnt lgkmcnt(0)
	v_mfma_f32_16x16x32_bf16 v[50:53], v[176:179], v[222:225], v[66:69]
	ds_read_b128 v[180:183], v171
	ds_read_b128 v[74:77], v144 offset:52224
	ds_read_b128 v[176:179], v144 offset:52288
	ds_read_b128 v[218:221], v250
	ds_read_b128 v[222:225], v251 offset:2304
	ds_read_b128 v[226:229], v250 offset:4608
	ds_read_b128 v[230:233], v251 offset:6912
	ds_read_b128 v[234:237], v250 offset:9216
	ds_read_b128 v[238:241], v251 offset:11520
	ds_read_b128 v[242:245], v250 offset:13824
	ds_read_b128 v[246:249], v251 offset:16128
	s_waitcnt lgkmcnt(10)
	v_pk_mul_f32 v[18:19], v[18:19], v[180:181]
	v_pk_mul_f32 v[20:21], v[20:21], v[182:183]
	v_pk_mul_f32 v[22:23], v[22:23], v[180:181]
	v_pk_mul_f32 v[24:25], v[24:25], v[182:183]
	v_pk_mul_f32 v[26:27], v[26:27], v[180:181]
	v_pk_mul_f32 v[28:29], v[28:29], v[182:183]
	v_pk_mul_f32 v[30:31], v[30:31], v[180:181]
	v_pk_mul_f32 v[32:33], v[32:33], v[182:183]
	v_pk_mul_f32 v[34:35], v[34:35], v[180:181]
	v_pk_mul_f32 v[36:37], v[36:37], v[182:183]
	v_pk_mul_f32 v[38:39], v[38:39], v[180:181]
	v_pk_mul_f32 v[40:41], v[40:41], v[182:183]
	v_pk_mul_f32 v[42:43], v[42:43], v[180:181]
	v_pk_mul_f32 v[44:45], v[44:45], v[182:183]
	v_pk_mul_f32 v[46:47], v[46:47], v[180:181]
	v_pk_mul_f32 v[48:49], v[48:49], v[182:183]
	v_mul_f32_e32 v16, v63, v63
	v_fmac_f32_e32 v16, v62, v62
	ds_read_b128 v[66:69], v250 offset:64
	ds_read_b128 v[70:73], v251 offset:2368
	s_waitcnt lgkmcnt(9)
	v_mfma_f32_16x16x32_bf16 v[18:21], v[74:77], v[218:221], v[18:21]
	ds_read_b128 v[218:221], v250 offset:4672
	s_waitcnt lgkmcnt(9)
	v_mfma_f32_16x16x32_bf16 v[22:25], v[74:77], v[222:225], v[22:25]
	ds_read_b128 v[222:225], v251 offset:6976
	s_waitcnt lgkmcnt(9)
	v_mfma_f32_16x16x32_bf16 v[26:29], v[74:77], v[226:229], v[26:29]
	ds_read_b128 v[226:229], v250 offset:9280
	s_waitcnt lgkmcnt(9)
	v_mfma_f32_16x16x32_bf16 v[30:33], v[74:77], v[230:233], v[30:33]
	ds_read_b128 v[230:233], v251 offset:11584
	s_waitcnt lgkmcnt(9)
	v_mfma_f32_16x16x32_bf16 v[34:37], v[74:77], v[234:237], v[34:37]
	ds_read_b128 v[234:237], v250 offset:13888
	s_waitcnt lgkmcnt(9)
	v_mfma_f32_16x16x32_bf16 v[38:41], v[74:77], v[238:241], v[38:41]
	ds_read_b128 v[238:241], v251 offset:16192
	s_waitcnt lgkmcnt(9)
	v_mfma_f32_16x16x32_bf16 v[42:45], v[74:77], v[242:245], v[42:45]
	s_waitcnt lgkmcnt(8)
	v_mfma_f32_16x16x32_bf16 v[46:49], v[74:77], v[246:249], v[46:49]
	s_waitcnt lgkmcnt(7)
	v_mfma_f32_16x16x32_bf16 v[18:21], v[176:179], v[66:69], v[18:21]
	s_waitcnt lgkmcnt(6)
	v_mfma_f32_16x16x32_bf16 v[22:25], v[176:179], v[70:73], v[22:25]
	s_waitcnt lgkmcnt(5)
	v_mfma_f32_16x16x32_bf16 v[26:29], v[176:179], v[218:221], v[26:29]
	s_waitcnt lgkmcnt(4)
	v_mfma_f32_16x16x32_bf16 v[30:33], v[176:179], v[222:225], v[30:33]
	s_waitcnt lgkmcnt(3)
	v_mfma_f32_16x16x32_bf16 v[34:37], v[176:179], v[226:229], v[34:37]
	s_waitcnt lgkmcnt(2)
	v_mfma_f32_16x16x32_bf16 v[38:41], v[176:179], v[230:233], v[38:41]
	s_waitcnt lgkmcnt(1)
	v_mfma_f32_16x16x32_bf16 v[42:45], v[176:179], v[234:237], v[42:45]
	s_waitcnt lgkmcnt(0)
	v_mfma_f32_16x16x32_bf16 v[46:49], v[176:179], v[238:241], v[46:49]
	s_nop 7
	v_mul_f32_e32 v66, v65, v65
	v_fmac_f32_e32 v66, v64, v64
	v_add_f32_e32 v16, v16, v66
	v_mul_f32_e32 v66, v59, v59
	v_mul_f32_e32 v67, v61, v61
	v_fmac_f32_e32 v66, v58, v58
	v_fmac_f32_e32 v67, v60, v60
	v_add_f32_e32 v66, v66, v67
	v_add_f32_e32 v16, v16, v66
	v_mul_f32_e32 v66, v55, v55
	v_mul_f32_e32 v67, v57, v57
	v_fmac_f32_e32 v66, v54, v54
	v_fmac_f32_e32 v67, v56, v56
	v_add_f32_e32 v66, v66, v67
	v_add_f32_e32 v16, v16, v66
	v_mul_f32_e32 v66, v51, v51
	v_mul_f32_e32 v67, v53, v53
	v_fmac_f32_e32 v66, v50, v50
	v_fmac_f32_e32 v67, v52, v52
	v_add_f32_e32 v66, v66, v67
	v_add_f32_e32 v16, v16, v66
	v_subrev_u32_e32 v66, 0x22b00, v173
	v_lshrrev_b32_e32 v67, 2, v188
	v_and_b32_e32 v67, 12, v67
	v_lshl_add_u32 v66, v66, 2, v67
	v_add_u32_e32 v66, 0x22b00, v66
	ds_write_b32 v66, v16
